# attention unit epilogues: all z / g_sub loads of a unit issued together instead of one global round trip per output chunk
# baseline (speedup 1.0000x reference)
; __device__ __forceinline__ unsigned cvt_pk_bf16(float lo, float hi) { f32x2_t v = {lo, hi}; bf16x2_t b = __builtin_convertvector(v, bf16x2_t); return __builtin_bit_cast(unsigned, b); }
; __device__ __forceinline__ float bf_lo(unsigned w) { return __uint_as_float(w << 16); }
; __device__ __forceinline__ float bf_hi(unsigned w) { return __uint_as_float(w & 0xffff0000u); }
; __device__ __forceinline__ float silu_f(float z) { return z * __builtin_amdgcn_rcpf(1.0f + fast_exp2(-1.4426950408889634f * z)); }
; __device__ __forceinline__ void diff_unit(LAS unsigned char* lds, const bf16_t* __restrict__ u, bf16_t* __restrict__ yz, float* __restrict__ oscr, const unsigned* __restrict__ kb, int b, int h, int qb, float lam, float slope2, const float* __restrict__ gsub, float out_scale) {
;     ...
;     float ss = 0.f;
; #pragma unroll
;     for (int c = 0; c < 4; ++c)
; #pragma unroll
;         for (int r = 0; r < 16; ++r) ss += o[c][r] * o[c][r];
;     ss += __shfl_xor(ss, 32);
;     const float rs = __builtin_amdgcn_rsqf(ss * (1.0f / 128.0f) + RMS_EPS) * out_scale;
;     { int tid_f = threadIdx.x; asm volatile("" : "+v"(tid_f));
;       const int hi_f = (tid_f >> 5) & 1, t_row_f = tw + (tid_f & 31);
;       const bf16_t* zp = u + (rowbase + t_row_f) * NIN + 3 * DM + h * 128 + 4 * hi_f;
;       bf16_t* yp = yz + (rowbase + t_row_f) * DM + h * 128 + 4 * hi_f;
;       const float* gp = gsub + 4 * hi_f;
; #pragma unroll
;       for (int c = 0; c < 4; ++c)
; #pragma unroll
;         for (int g = 0; g < 4; ++g) { const u32x2 zz = *(const u32x2*)(zp + 32 * c + 8 * g); const f32x4 gg = *(const f32x4*)(gp + 32 * c + 8 * g);
;             const float a0 = o[c][4 * g + 0] * rs * gg[0] * silu_f(bf_lo(zz.x)), a1 = o[c][4 * g + 1] * rs * gg[1] * silu_f(bf_hi(zz.x));
;             const float a2 = o[c][4 * g + 2] * rs * gg[2] * silu_f(bf_lo(zz.y)), a3 = o[c][4 * g + 3] * rs * gg[3] * silu_f(bf_hi(zz.y));
;             u32x2 w; w.x = cvt_pk_bf16(a0, a1); w.y = cvt_pk_bf16(a2, a3); *(u32x2*)(yp + 32 * c + 8 * g) = w; } }
.LBB0_207:
	v_mul_f32_e32 v0, v115, v115
	v_fmac_f32_e32 v0, v114, v114
	v_fmac_f32_e32 v0, v116, v116
	v_fmac_f32_e32 v0, v117, v117
	v_fmac_f32_e32 v0, v118, v118
	v_fmac_f32_e32 v0, v119, v119
	v_fmac_f32_e32 v0, v120, v120
	v_fmac_f32_e32 v0, v121, v121
	v_fmac_f32_e32 v0, v122, v122
	v_fmac_f32_e32 v0, v123, v123
	v_fmac_f32_e32 v0, v124, v124
	v_fmac_f32_e32 v0, v125, v125
	v_fmac_f32_e32 v0, v126, v126
	v_fmac_f32_e32 v0, v127, v127
	v_fmac_f32_e32 v0, v128, v128
	v_fmac_f32_e32 v0, v129, v129
	v_fmac_f32_e32 v0, v98, v98
	v_fmac_f32_e32 v0, v99, v99
	v_fmac_f32_e32 v0, v100, v100
	v_fmac_f32_e32 v0, v101, v101
	v_fmac_f32_e32 v0, v102, v102
	v_fmac_f32_e32 v0, v103, v103
	v_fmac_f32_e32 v0, v104, v104
	v_fmac_f32_e32 v0, v105, v105
	v_fmac_f32_e32 v0, v106, v106
	v_fmac_f32_e32 v0, v107, v107
	v_fmac_f32_e32 v0, v108, v108
	v_fmac_f32_e32 v0, v109, v109
	v_fmac_f32_e32 v0, v110, v110
	v_fmac_f32_e32 v0, v111, v111
	v_fmac_f32_e32 v0, v112, v112
	v_fmac_f32_e32 v0, v113, v113
	v_fmac_f32_e32 v0, v82, v82
	v_fmac_f32_e32 v0, v83, v83
	v_fmac_f32_e32 v0, v84, v84
	v_fmac_f32_e32 v0, v85, v85
	v_fmac_f32_e32 v0, v86, v86
	v_fmac_f32_e32 v0, v87, v87
	v_fmac_f32_e32 v0, v88, v88
	v_fmac_f32_e32 v0, v89, v89
	v_fmac_f32_e32 v0, v90, v90
	v_fmac_f32_e32 v0, v91, v91
	v_fmac_f32_e32 v0, v92, v92
	v_fmac_f32_e32 v0, v93, v93
	v_fmac_f32_e32 v0, v94, v94
	v_fmac_f32_e32 v0, v95, v95
	v_fmac_f32_e32 v0, v96, v96
	v_fmac_f32_e32 v0, v97, v97
	v_fmac_f32_e32 v0, v66, v66
	v_fmac_f32_e32 v0, v67, v67
	v_fmac_f32_e32 v0, v68, v68
	v_fmac_f32_e32 v0, v69, v69
	v_fmac_f32_e32 v0, v70, v70
	v_fmac_f32_e32 v0, v71, v71
	v_fmac_f32_e32 v0, v72, v72
	v_fmac_f32_e32 v0, v73, v73
	v_fmac_f32_e32 v0, v74, v74
	v_fmac_f32_e32 v0, v75, v75
	v_pk_mul_f32 v[6:7], v[76:77], v[76:77]
	v_pk_mul_f32 v[4:5], v[78:79], v[78:79]
	v_add_f32_e32 v0, v6, v0
	v_add_f32_e32 v0, v7, v0
	v_add_f32_e32 v0, v4, v0
	v_pk_mul_f32 v[2:3], v[80:81], v[80:81]
	v_add_f32_e32 v0, v5, v0
	v_add_f32_e32 v0, v2, v0
	v_add_f32_e32 v0, v3, v0
	ds_bpermute_b32 v2, v143, v0
	v_readlane_b32 s2, v232, 54
	v_readlane_b32 s30, v233, 37
	s_mov_b64 s[4:5], 0
	v_readlane_b32 s31, v233, 38
	s_waitcnt lgkmcnt(0)
	v_add_f32_e32 v0, v0, v2
	v_fmamk_f32 v0, v0, 0x3c000000, v160
	v_rsq_f32_e32 v0, v0
	s_nop 0
	v_mul_f32_e32 v6, v144, v0
	v_mov_b32_e32 v0, v140
	s_nop 0
	v_and_or_b32 v2, v0, 31, s2
	v_readlane_b32 s2, v232, 52
	v_ashrrev_i32_e32 v3, 31, v2
	v_readlane_b32 s3, v232, 53
	v_lshrrev_b32_e32 v0, 3, v0
	v_and_b32_e32 v7, 4, v0
	v_lshl_add_u64 v[4:5], v[2:3], 0, s[2:3]
	v_lshlrev_b64 v[2:3], 13, v[4:5]
	v_readlane_b32 s2, v232, 51
	v_lshl_add_u64 v[2:3], s[34:35], 0, v[2:3]
	s_lshl_b32 s96, s2, 1
	v_lshl_add_u64 v[2:3], v[2:3], 0, s[96:97]
	v_lshlrev_b32_e32 v0, 1, v7
	v_lshl_add_u64 v[10:11], v[2:3], 0, v[0:1]
	s_mov_b64 s[2:3], 0x1800
	v_lshl_add_u64 v[2:3], v[10:11], 0, s[2:3]
	v_readlane_b32 s2, v233, 39
	v_lshlrev_b64 v[4:5], 11, v[4:5]
	v_readlane_b32 s3, v233, 40
	v_pk_mul_f32 v[18:19], v[114:115], v[6:7] op_sel_hi:[1,0]
	s_nop 0
	v_lshl_add_u64 v[4:5], s[2:3], 0, v[4:5]
	v_lshl_add_u64 v[4:5], v[4:5], 0, s[96:97]
	s_movk_i32 s2, 0x1000
	v_lshl_add_u64 v[8:9], v[4:5], 0, v[0:1]
	v_add_co_u32_e32 v4, vcc, s2, v10
	v_lshlrev_b32_e32 v0, 2, v7
	s_nop 0
	v_addc_co_u32_e32 v5, vcc, 0, v11, vcc
	global_load_dwordx2 v[20:21], v[2:3], off
	global_load_dwordx2 v[22:23], v[2:3], off offset:16
	global_load_dwordx2 v[24:25], v[2:3], off offset:32
	global_load_dwordx2 v[26:27], v[2:3], off offset:48
	global_load_dwordx2 v[28:29], v[2:3], off offset:64
	global_load_dwordx2 v[30:31], v[2:3], off offset:80
	global_load_dwordx2 v[32:33], v[2:3], off offset:96
	global_load_dwordx2 v[34:35], v[2:3], off offset:112
	global_load_dwordx2 v[36:37], v[2:3], off offset:128
	global_load_dwordx2 v[38:39], v[2:3], off offset:144
	global_load_dwordx2 v[40:41], v[2:3], off offset:160
	global_load_dwordx2 v[42:43], v[2:3], off offset:176
	global_load_dwordx2 v[44:45], v[2:3], off offset:192
	global_load_dwordx2 v[46:47], v[2:3], off offset:208
	global_load_dwordx2 v[48:49], v[2:3], off offset:224
	global_load_dwordx2 v[50:51], v[2:3], off offset:240
	global_load_dwordx4 v[172:175], v0, s[94:95]
	global_load_dwordx4 v[176:179], v0, s[94:95] offset:32
	global_load_dwordx4 v[180:183], v0, s[94:95] offset:64
	global_load_dwordx4 v[184:187], v0, s[94:95] offset:96
	global_load_dwordx4 v[188:191], v0, s[94:95] offset:128
	global_load_dwordx4 v[192:195], v0, s[94:95] offset:160
	global_load_dwordx4 v[196:199], v0, s[94:95] offset:192
	global_load_dwordx4 v[200:203], v0, s[94:95] offset:224
	global_load_dwordx4 v[204:207], v0, s[94:95] offset:256
	global_load_dwordx4 v[208:211], v0, s[94:95] offset:288
	global_load_dwordx4 v[212:215], v0, s[94:95] offset:320
	global_load_dwordx4 v[216:219], v0, s[94:95] offset:352
	global_load_dwordx4 v[220:223], v0, s[94:95] offset:384
	global_load_dwordx4 v[224:227], v0, s[94:95] offset:416
	global_load_dwordx4 v[52:55], v0, s[94:95] offset:448
	global_load_dwordx4 v[56:59], v0, s[94:95] offset:480
	s_nop 0
	s_waitcnt vmcnt(0)
; __device__ __forceinline__ unsigned cvt_pk_bf16(float lo, float hi) { f32x2_t v = {lo, hi}; bf16x2_t b = __builtin_convertvector(v, bf16x2_t); return __builtin_bit_cast(unsigned, b); }
; __device__ __forceinline__ float bf_lo(unsigned w) { return __uint_as_float(w << 16); }
; __device__ __forceinline__ float bf_hi(unsigned w) { return __uint_as_float(w & 0xffff0000u); }
; __device__ __forceinline__ float silu_f(float z) { return z * __builtin_amdgcn_rcpf(1.0f + fast_exp2(-1.4426950408889634f * z)); }
; __device__ __forceinline__ void diff_unit(LAS unsigned char* lds, const bf16_t* __restrict__ u, bf16_t* __restrict__ yz, float* __restrict__ oscr, const unsigned* __restrict__ kb, int b, int h, int qb, float lam, float slope2, const float* __restrict__ gsub, float out_scale) {
;     ...
; #pragma unroll
;       for (int c = 0; c < 4; ++c)
; #pragma unroll
;         for (int g = 0; g < 4; ++g) { const u32x2 zz = *(const u32x2*)(zp + 32 * c + 8 * g); const f32x4 gg = *(const f32x4*)(gp + 32 * c + 8 * g);
;             const float a0 = o[c][4 * g + 0] * rs * gg[0] * silu_f(bf_lo(zz.x)), a1 = o[c][4 * g + 1] * rs * gg[1] * silu_f(bf_hi(zz.x));
;             const float a2 = o[c][4 * g + 2] * rs * gg[2] * silu_f(bf_lo(zz.y)), a3 = o[c][4 * g + 3] * rs * gg[3] * silu_f(bf_hi(zz.y));
;             u32x2 w; w.x = cvt_pk_bf16(a0, a1); w.y = cvt_pk_bf16(a2, a3); *(u32x2*)(yp + 32 * c + 8 * g) = w; } }
	v_mov_b32_e32 v4, v20
	v_mov_b32_e32 v5, v21
	v_mov_b32_e32 v10, v172
	v_mov_b32_e32 v11, v173
	v_mov_b32_e32 v12, v174
	v_mov_b32_e32 v13, v175
	v_lshlrev_b32_e32 v14, 16, v4
	v_and_b32_e32 v15, 0xffff0000, v4
	v_mul_f32_e32 v4, 0xbfb8aa3b, v14
	v_exp_f32_e32 v4, v4
	v_pk_mul_f32 v[10:11], v[10:11], v[18:19]
	v_add_f32_e32 v4, 1.0, v4
	v_rcp_f32_e32 v16, v4
	v_mul_f32_e32 v4, 0xbfb8aa3b, v15
	v_exp_f32_e32 v4, v4
	s_nop 0
	v_add_f32_e32 v4, 1.0, v4
	v_rcp_f32_e32 v17, v4
	v_lshlrev_b32_e32 v4, 16, v5
	v_mul_f32_e32 v7, 0xbfb8aa3b, v4
	v_exp_f32_e32 v7, v7
	v_pk_mul_f32 v[14:15], v[16:17], v[14:15]
	v_and_b32_e32 v5, 0xffff0000, v5
	v_pk_mul_f32 v[10:11], v[10:11], v[14:15]
	v_add_f32_e32 v7, 1.0, v7
	v_rcp_f32_e32 v14, v7
	v_pk_mul_f32 v[16:17], v[116:117], v[6:7] op_sel_hi:[1,0]
	v_mul_f32_e32 v7, 0xbfb8aa3b, v5
	v_exp_f32_e32 v7, v7
	v_pk_mul_f32 v[12:13], v[12:13], v[16:17]
	v_cvt_pk_bf16_f32 v10, v10, v11
	v_add_f32_e32 v7, 1.0, v7
	v_rcp_f32_e32 v15, v7
	v_pk_mul_f32 v[18:19], v[118:119], v[6:7] op_sel_hi:[1,0]
	v_pk_mul_f32 v[4:5], v[14:15], v[4:5]
	s_nop 0
	v_pk_mul_f32 v[4:5], v[12:13], v[4:5]
	s_nop 0
	v_cvt_pk_bf16_f32 v11, v4, v5
	global_store_dwordx2 v[8:9], v[10:11], off
	v_mov_b32_e32 v4, v22
	v_mov_b32_e32 v5, v23
	s_nop 0
	v_mov_b32_e32 v10, v176
	v_mov_b32_e32 v11, v177
	v_mov_b32_e32 v12, v178
	v_mov_b32_e32 v13, v179
	v_lshlrev_b32_e32 v14, 16, v4
	v_and_b32_e32 v15, 0xffff0000, v4
	v_mul_f32_e32 v4, 0xbfb8aa3b, v14
	v_exp_f32_e32 v4, v4
	v_pk_mul_f32 v[10:11], v[10:11], v[18:19]
	v_add_f32_e32 v4, 1.0, v4
	v_rcp_f32_e32 v16, v4
	v_mul_f32_e32 v4, 0xbfb8aa3b, v15
	v_exp_f32_e32 v4, v4
	s_nop 0
	v_add_f32_e32 v4, 1.0, v4
	v_rcp_f32_e32 v17, v4
	v_lshlrev_b32_e32 v4, 16, v5
	v_mul_f32_e32 v7, 0xbfb8aa3b, v4
	v_exp_f32_e32 v7, v7
	v_pk_mul_f32 v[14:15], v[16:17], v[14:15]
	v_and_b32_e32 v5, 0xffff0000, v5
	v_pk_mul_f32 v[10:11], v[10:11], v[14:15]
	v_add_f32_e32 v7, 1.0, v7
	v_rcp_f32_e32 v14, v7
	v_pk_mul_f32 v[16:17], v[120:121], v[6:7] op_sel_hi:[1,0]
	v_mul_f32_e32 v7, 0xbfb8aa3b, v5
	v_exp_f32_e32 v7, v7
	v_pk_mul_f32 v[12:13], v[12:13], v[16:17]
	v_cvt_pk_bf16_f32 v10, v10, v11
	v_add_f32_e32 v7, 1.0, v7
	v_rcp_f32_e32 v15, v7
	v_pk_mul_f32 v[18:19], v[122:123], v[6:7] op_sel_hi:[1,0]
	v_pk_mul_f32 v[4:5], v[14:15], v[4:5]
	s_nop 0
	v_pk_mul_f32 v[4:5], v[12:13], v[4:5]
	s_nop 0
	v_cvt_pk_bf16_f32 v11, v4, v5
	global_store_dwordx2 v[8:9], v[10:11], off offset:16
	v_mov_b32_e32 v4, v24
	v_mov_b32_e32 v5, v25
	s_nop 0
	v_mov_b32_e32 v10, v180
	v_mov_b32_e32 v11, v181
	v_mov_b32_e32 v12, v182
	v_mov_b32_e32 v13, v183
	v_lshlrev_b32_e32 v14, 16, v4
	v_and_b32_e32 v15, 0xffff0000, v4
	v_mul_f32_e32 v4, 0xbfb8aa3b, v14
	v_exp_f32_e32 v4, v4
	v_pk_mul_f32 v[10:11], v[18:19], v[10:11]
	v_add_f32_e32 v4, 1.0, v4
	v_rcp_f32_e32 v16, v4
	v_mul_f32_e32 v4, 0xbfb8aa3b, v15
	v_exp_f32_e32 v4, v4
	s_nop 0
	v_add_f32_e32 v4, 1.0, v4
	v_rcp_f32_e32 v17, v4
	v_lshlrev_b32_e32 v4, 16, v5
	v_mul_f32_e32 v7, 0xbfb8aa3b, v4
	v_exp_f32_e32 v7, v7
	v_pk_mul_f32 v[14:15], v[16:17], v[14:15]
	v_and_b32_e32 v5, 0xffff0000, v5
	v_pk_mul_f32 v[10:11], v[10:11], v[14:15]
	v_add_f32_e32 v7, 1.0, v7
	v_rcp_f32_e32 v14, v7
	v_pk_mul_f32 v[16:17], v[124:125], v[6:7] op_sel_hi:[1,0]
	v_mul_f32_e32 v7, 0xbfb8aa3b, v5
	v_exp_f32_e32 v7, v7
	v_pk_mul_f32 v[12:13], v[16:17], v[12:13]
	v_cvt_pk_bf16_f32 v10, v10, v11
	v_add_f32_e32 v7, 1.0, v7
	v_rcp_f32_e32 v15, v7
	v_pk_mul_f32 v[18:19], v[126:127], v[6:7] op_sel_hi:[1,0]
	v_pk_mul_f32 v[4:5], v[14:15], v[4:5]
	s_nop 0
	v_pk_mul_f32 v[4:5], v[12:13], v[4:5]
	s_nop 0
	v_cvt_pk_bf16_f32 v11, v4, v5
	global_store_dwordx2 v[8:9], v[10:11], off offset:32
	v_mov_b32_e32 v4, v26
	v_mov_b32_e32 v5, v27
	s_nop 0
	v_mov_b32_e32 v10, v184
	v_mov_b32_e32 v11, v185
	v_mov_b32_e32 v12, v186
	v_mov_b32_e32 v13, v187
	v_lshlrev_b32_e32 v14, 16, v4
	v_and_b32_e32 v15, 0xffff0000, v4
	v_mul_f32_e32 v4, 0xbfb8aa3b, v14
	v_exp_f32_e32 v4, v4
	v_pk_mul_f32 v[10:11], v[18:19], v[10:11]
	v_add_f32_e32 v4, 1.0, v4
	v_rcp_f32_e32 v16, v4
	v_mul_f32_e32 v4, 0xbfb8aa3b, v15
	v_exp_f32_e32 v4, v4
	s_nop 0
	v_add_f32_e32 v4, 1.0, v4
	v_rcp_f32_e32 v17, v4
	v_lshlrev_b32_e32 v4, 16, v5
	v_mul_f32_e32 v7, 0xbfb8aa3b, v4
	v_exp_f32_e32 v7, v7
	v_pk_mul_f32 v[14:15], v[16:17], v[14:15]
	v_and_b32_e32 v5, 0xffff0000, v5
	v_pk_mul_f32 v[10:11], v[10:11], v[14:15]
	v_add_f32_e32 v7, 1.0, v7
	v_rcp_f32_e32 v14, v7
	v_pk_mul_f32 v[16:17], v[128:129], v[6:7] op_sel_hi:[1,0]
	v_mul_f32_e32 v7, 0xbfb8aa3b, v5
	v_exp_f32_e32 v7, v7
	v_pk_mul_f32 v[12:13], v[16:17], v[12:13]
	v_cvt_pk_bf16_f32 v10, v10, v11
	v_add_f32_e32 v7, 1.0, v7
	v_rcp_f32_e32 v15, v7
	v_pk_mul_f32 v[18:19], v[98:99], v[6:7] op_sel_hi:[1,0]
	v_pk_mul_f32 v[4:5], v[14:15], v[4:5]
	s_nop 0
	v_pk_mul_f32 v[4:5], v[12:13], v[4:5]
	s_nop 0
	v_cvt_pk_bf16_f32 v11, v4, v5
	global_store_dwordx2 v[8:9], v[10:11], off offset:48
	v_mov_b32_e32 v4, v28
	v_mov_b32_e32 v5, v29
	s_nop 0
	v_mov_b32_e32 v10, v188
	v_mov_b32_e32 v11, v189
	v_mov_b32_e32 v12, v190
	v_mov_b32_e32 v13, v191
	v_lshlrev_b32_e32 v14, 16, v4
	v_and_b32_e32 v15, 0xffff0000, v4
	v_mul_f32_e32 v4, 0xbfb8aa3b, v14
	v_exp_f32_e32 v4, v4
	v_pk_mul_f32 v[10:11], v[18:19], v[10:11]
	v_add_f32_e32 v4, 1.0, v4
	v_rcp_f32_e32 v16, v4
	v_mul_f32_e32 v4, 0xbfb8aa3b, v15
	v_exp_f32_e32 v4, v4
	s_nop 0
	v_add_f32_e32 v4, 1.0, v4
	v_rcp_f32_e32 v17, v4
	v_lshlrev_b32_e32 v4, 16, v5
	v_mul_f32_e32 v7, 0xbfb8aa3b, v4
	v_exp_f32_e32 v7, v7
	v_pk_mul_f32 v[14:15], v[16:17], v[14:15]
	v_and_b32_e32 v5, 0xffff0000, v5
	v_pk_mul_f32 v[10:11], v[10:11], v[14:15]
	v_add_f32_e32 v7, 1.0, v7
	v_rcp_f32_e32 v14, v7
; __device__ __forceinline__ unsigned cvt_pk_bf16(float lo, float hi) { f32x2_t v = {lo, hi}; bf16x2_t b = __builtin_convertvector(v, bf16x2_t); return __builtin_bit_cast(unsigned, b); }
; __device__ __forceinline__ float bf_lo(unsigned w) { return __uint_as_float(w << 16); }
; __device__ __forceinline__ float bf_hi(unsigned w) { return __uint_as_float(w & 0xffff0000u); }
; __device__ __forceinline__ float silu_f(float z) { return z * __builtin_amdgcn_rcpf(1.0f + fast_exp2(-1.4426950408889634f * z)); }
; __device__ __forceinline__ void diff_unit(LAS unsigned char* lds, const bf16_t* __restrict__ u, bf16_t* __restrict__ yz, float* __restrict__ oscr, const unsigned* __restrict__ kb, int b, int h, int qb, float lam, float slope2, const float* __restrict__ gsub, float out_scale) {
;     ...
; #pragma unroll
;       for (int c = 0; c < 4; ++c)
; #pragma unroll
;         for (int g = 0; g < 4; ++g) { const u32x2 zz = *(const u32x2*)(zp + 32 * c + 8 * g); const f32x4 gg = *(const f32x4*)(gp + 32 * c + 8 * g);
;             const float a0 = o[c][4 * g + 0] * rs * gg[0] * silu_f(bf_lo(zz.x)), a1 = o[c][4 * g + 1] * rs * gg[1] * silu_f(bf_hi(zz.x));
;             const float a2 = o[c][4 * g + 2] * rs * gg[2] * silu_f(bf_lo(zz.y)), a3 = o[c][4 * g + 3] * rs * gg[3] * silu_f(bf_hi(zz.y));
;             u32x2 w; w.x = cvt_pk_bf16(a0, a1); w.y = cvt_pk_bf16(a2, a3); *(u32x2*)(yp + 32 * c + 8 * g) = w; } }
	v_pk_mul_f32 v[16:17], v[100:101], v[6:7] op_sel_hi:[1,0]
	v_mul_f32_e32 v7, 0xbfb8aa3b, v5
	v_exp_f32_e32 v7, v7
	v_pk_mul_f32 v[12:13], v[16:17], v[12:13]
	v_cvt_pk_bf16_f32 v10, v10, v11
	v_add_f32_e32 v7, 1.0, v7
	v_rcp_f32_e32 v15, v7
	v_pk_mul_f32 v[18:19], v[102:103], v[6:7] op_sel_hi:[1,0]
	v_pk_mul_f32 v[4:5], v[14:15], v[4:5]
	s_nop 0
	v_pk_mul_f32 v[4:5], v[12:13], v[4:5]
	s_nop 0
	v_cvt_pk_bf16_f32 v11, v4, v5
	global_store_dwordx2 v[8:9], v[10:11], off offset:64
	v_mov_b32_e32 v4, v30
	v_mov_b32_e32 v5, v31
	s_nop 0
	v_mov_b32_e32 v10, v192
	v_mov_b32_e32 v11, v193
	v_mov_b32_e32 v12, v194
	v_mov_b32_e32 v13, v195
	v_lshlrev_b32_e32 v14, 16, v4
	v_and_b32_e32 v15, 0xffff0000, v4
	v_mul_f32_e32 v4, 0xbfb8aa3b, v14
	v_exp_f32_e32 v4, v4
	v_pk_mul_f32 v[10:11], v[18:19], v[10:11]
	v_add_f32_e32 v4, 1.0, v4
	v_rcp_f32_e32 v16, v4
	v_mul_f32_e32 v4, 0xbfb8aa3b, v15
	v_exp_f32_e32 v4, v4
	s_nop 0
	v_add_f32_e32 v4, 1.0, v4
	v_rcp_f32_e32 v17, v4
	v_lshlrev_b32_e32 v4, 16, v5
	v_mul_f32_e32 v7, 0xbfb8aa3b, v4
	v_exp_f32_e32 v7, v7
	v_pk_mul_f32 v[14:15], v[16:17], v[14:15]
	v_and_b32_e32 v5, 0xffff0000, v5
	v_pk_mul_f32 v[10:11], v[10:11], v[14:15]
	v_add_f32_e32 v7, 1.0, v7
	v_rcp_f32_e32 v14, v7
	v_pk_mul_f32 v[16:17], v[104:105], v[6:7] op_sel_hi:[1,0]
	v_mul_f32_e32 v7, 0xbfb8aa3b, v5
	v_exp_f32_e32 v7, v7
	v_pk_mul_f32 v[12:13], v[16:17], v[12:13]
	v_cvt_pk_bf16_f32 v10, v10, v11
	v_add_f32_e32 v7, 1.0, v7
	v_rcp_f32_e32 v15, v7
	v_pk_mul_f32 v[18:19], v[106:107], v[6:7] op_sel_hi:[1,0]
	v_pk_mul_f32 v[4:5], v[14:15], v[4:5]
	s_nop 0
	v_pk_mul_f32 v[4:5], v[12:13], v[4:5]
	s_nop 0
	v_cvt_pk_bf16_f32 v11, v4, v5
	global_store_dwordx2 v[8:9], v[10:11], off offset:80
	v_mov_b32_e32 v4, v32
	v_mov_b32_e32 v5, v33
	s_nop 0
	v_mov_b32_e32 v10, v196
	v_mov_b32_e32 v11, v197
	v_mov_b32_e32 v12, v198
	v_mov_b32_e32 v13, v199
	v_lshlrev_b32_e32 v14, 16, v4
	v_and_b32_e32 v15, 0xffff0000, v4
	v_mul_f32_e32 v4, 0xbfb8aa3b, v14
	v_exp_f32_e32 v4, v4
	v_pk_mul_f32 v[10:11], v[18:19], v[10:11]
	v_add_f32_e32 v4, 1.0, v4
	v_rcp_f32_e32 v16, v4
	v_mul_f32_e32 v4, 0xbfb8aa3b, v15
	v_exp_f32_e32 v4, v4
	s_nop 0
	v_add_f32_e32 v4, 1.0, v4
	v_rcp_f32_e32 v17, v4
	v_lshlrev_b32_e32 v4, 16, v5
	v_mul_f32_e32 v7, 0xbfb8aa3b, v4
	v_exp_f32_e32 v7, v7
	v_pk_mul_f32 v[14:15], v[16:17], v[14:15]
	v_and_b32_e32 v5, 0xffff0000, v5
	v_pk_mul_f32 v[10:11], v[10:11], v[14:15]
	v_add_f32_e32 v7, 1.0, v7
	v_rcp_f32_e32 v14, v7
	v_pk_mul_f32 v[16:17], v[108:109], v[6:7] op_sel_hi:[1,0]
	v_mul_f32_e32 v7, 0xbfb8aa3b, v5
	v_exp_f32_e32 v7, v7
	v_pk_mul_f32 v[12:13], v[16:17], v[12:13]
	v_cvt_pk_bf16_f32 v10, v10, v11
	v_add_f32_e32 v7, 1.0, v7
	v_rcp_f32_e32 v15, v7
	v_pk_mul_f32 v[18:19], v[110:111], v[6:7] op_sel_hi:[1,0]
	v_pk_mul_f32 v[4:5], v[14:15], v[4:5]
	s_nop 0
	v_pk_mul_f32 v[4:5], v[12:13], v[4:5]
	s_nop 0
	v_cvt_pk_bf16_f32 v11, v4, v5
	global_store_dwordx2 v[8:9], v[10:11], off offset:96
	v_mov_b32_e32 v4, v34
	v_mov_b32_e32 v5, v35
	s_nop 0
	v_mov_b32_e32 v10, v200
	v_mov_b32_e32 v11, v201
	v_mov_b32_e32 v12, v202
	v_mov_b32_e32 v13, v203
	v_lshlrev_b32_e32 v14, 16, v4
	v_and_b32_e32 v15, 0xffff0000, v4
	v_mul_f32_e32 v4, 0xbfb8aa3b, v14
	v_exp_f32_e32 v4, v4
	v_pk_mul_f32 v[10:11], v[18:19], v[10:11]
	v_add_f32_e32 v4, 1.0, v4
	v_rcp_f32_e32 v16, v4
	v_mul_f32_e32 v4, 0xbfb8aa3b, v15
	v_exp_f32_e32 v4, v4
	s_nop 0
	v_add_f32_e32 v4, 1.0, v4
	v_rcp_f32_e32 v17, v4
	v_lshlrev_b32_e32 v4, 16, v5
	v_mul_f32_e32 v7, 0xbfb8aa3b, v4
	v_exp_f32_e32 v7, v7
	v_pk_mul_f32 v[14:15], v[16:17], v[14:15]
	v_and_b32_e32 v5, 0xffff0000, v5
	v_pk_mul_f32 v[10:11], v[10:11], v[14:15]
	v_add_f32_e32 v7, 1.0, v7
	v_rcp_f32_e32 v14, v7
	v_pk_mul_f32 v[16:17], v[112:113], v[6:7] op_sel_hi:[1,0]
	v_mul_f32_e32 v7, 0xbfb8aa3b, v5
	v_exp_f32_e32 v7, v7
	v_pk_mul_f32 v[12:13], v[16:17], v[12:13]
	v_cvt_pk_bf16_f32 v10, v10, v11
	v_add_f32_e32 v7, 1.0, v7
	v_rcp_f32_e32 v15, v7
	v_pk_mul_f32 v[18:19], v[82:83], v[6:7] op_sel_hi:[1,0]
	v_pk_mul_f32 v[4:5], v[14:15], v[4:5]
	s_nop 0
	v_pk_mul_f32 v[4:5], v[12:13], v[4:5]
	s_nop 0
	v_cvt_pk_bf16_f32 v11, v4, v5
	global_store_dwordx2 v[8:9], v[10:11], off offset:112
	v_mov_b32_e32 v4, v36
	v_mov_b32_e32 v5, v37
	s_nop 0
	v_mov_b32_e32 v10, v204
	v_mov_b32_e32 v11, v205
	v_mov_b32_e32 v12, v206
	v_mov_b32_e32 v13, v207
	v_lshlrev_b32_e32 v14, 16, v4
	v_and_b32_e32 v15, 0xffff0000, v4
	v_mul_f32_e32 v4, 0xbfb8aa3b, v14
	v_exp_f32_e32 v4, v4
	v_pk_mul_f32 v[10:11], v[18:19], v[10:11]
	v_add_f32_e32 v4, 1.0, v4
	v_rcp_f32_e32 v16, v4
	v_mul_f32_e32 v4, 0xbfb8aa3b, v15
	v_exp_f32_e32 v4, v4
	s_nop 0
	v_add_f32_e32 v4, 1.0, v4
	v_rcp_f32_e32 v17, v4
	v_lshlrev_b32_e32 v4, 16, v5
	v_mul_f32_e32 v7, 0xbfb8aa3b, v4
	v_exp_f32_e32 v7, v7
	v_pk_mul_f32 v[14:15], v[16:17], v[14:15]
	v_and_b32_e32 v5, 0xffff0000, v5
	v_pk_mul_f32 v[10:11], v[10:11], v[14:15]
	v_add_f32_e32 v7, 1.0, v7
	v_rcp_f32_e32 v14, v7
	v_pk_mul_f32 v[16:17], v[84:85], v[6:7] op_sel_hi:[1,0]
	v_mul_f32_e32 v7, 0xbfb8aa3b, v5
	v_exp_f32_e32 v7, v7
	v_pk_mul_f32 v[12:13], v[16:17], v[12:13]
	v_cvt_pk_bf16_f32 v10, v10, v11
	v_add_f32_e32 v7, 1.0, v7
	v_rcp_f32_e32 v15, v7
	v_pk_mul_f32 v[18:19], v[86:87], v[6:7] op_sel_hi:[1,0]
	v_pk_mul_f32 v[4:5], v[14:15], v[4:5]
	s_nop 0
	v_pk_mul_f32 v[4:5], v[12:13], v[4:5]
	s_nop 0
	v_cvt_pk_bf16_f32 v11, v4, v5
	global_store_dwordx2 v[8:9], v[10:11], off offset:128
	v_mov_b32_e32 v4, v38
	v_mov_b32_e32 v5, v39
	s_nop 0
	v_mov_b32_e32 v10, v208
	v_mov_b32_e32 v11, v209
	v_mov_b32_e32 v12, v210
	v_mov_b32_e32 v13, v211
	v_lshlrev_b32_e32 v14, 16, v4
	v_and_b32_e32 v15, 0xffff0000, v4
	v_mul_f32_e32 v4, 0xbfb8aa3b, v14
; __device__ __forceinline__ unsigned cvt_pk_bf16(float lo, float hi) { f32x2_t v = {lo, hi}; bf16x2_t b = __builtin_convertvector(v, bf16x2_t); return __builtin_bit_cast(unsigned, b); }
; __device__ __forceinline__ float bf_lo(unsigned w) { return __uint_as_float(w << 16); }
; __device__ __forceinline__ float bf_hi(unsigned w) { return __uint_as_float(w & 0xffff0000u); }
; __device__ __forceinline__ float silu_f(float z) { return z * __builtin_amdgcn_rcpf(1.0f + fast_exp2(-1.4426950408889634f * z)); }
; __device__ __forceinline__ void diff_unit(LAS unsigned char* lds, const bf16_t* __restrict__ u, bf16_t* __restrict__ yz, float* __restrict__ oscr, const unsigned* __restrict__ kb, int b, int h, int qb, float lam, float slope2, const float* __restrict__ gsub, float out_scale) {
;     ...
; #pragma unroll
;       for (int c = 0; c < 4; ++c)
; #pragma unroll
;         for (int g = 0; g < 4; ++g) { const u32x2 zz = *(const u32x2*)(zp + 32 * c + 8 * g); const f32x4 gg = *(const f32x4*)(gp + 32 * c + 8 * g);
;             const float a0 = o[c][4 * g + 0] * rs * gg[0] * silu_f(bf_lo(zz.x)), a1 = o[c][4 * g + 1] * rs * gg[1] * silu_f(bf_hi(zz.x));
;             const float a2 = o[c][4 * g + 2] * rs * gg[2] * silu_f(bf_lo(zz.y)), a3 = o[c][4 * g + 3] * rs * gg[3] * silu_f(bf_hi(zz.y));
;             u32x2 w; w.x = cvt_pk_bf16(a0, a1); w.y = cvt_pk_bf16(a2, a3); *(u32x2*)(yp + 32 * c + 8 * g) = w; } }
	v_exp_f32_e32 v4, v4
	v_pk_mul_f32 v[10:11], v[18:19], v[10:11]
	v_add_f32_e32 v4, 1.0, v4
	v_rcp_f32_e32 v16, v4
	v_mul_f32_e32 v4, 0xbfb8aa3b, v15
	v_exp_f32_e32 v4, v4
	s_nop 0
	v_add_f32_e32 v4, 1.0, v4
	v_rcp_f32_e32 v17, v4
	v_lshlrev_b32_e32 v4, 16, v5
	v_mul_f32_e32 v7, 0xbfb8aa3b, v4
	v_exp_f32_e32 v7, v7
	v_pk_mul_f32 v[14:15], v[16:17], v[14:15]
	v_and_b32_e32 v5, 0xffff0000, v5
	v_pk_mul_f32 v[10:11], v[10:11], v[14:15]
	v_add_f32_e32 v7, 1.0, v7
	v_rcp_f32_e32 v14, v7
	v_pk_mul_f32 v[16:17], v[88:89], v[6:7] op_sel_hi:[1,0]
	v_mul_f32_e32 v7, 0xbfb8aa3b, v5
	v_exp_f32_e32 v7, v7
	v_pk_mul_f32 v[12:13], v[16:17], v[12:13]
	v_cvt_pk_bf16_f32 v10, v10, v11
	v_add_f32_e32 v7, 1.0, v7
	v_rcp_f32_e32 v15, v7
	v_pk_mul_f32 v[18:19], v[90:91], v[6:7] op_sel_hi:[1,0]
	v_pk_mul_f32 v[4:5], v[14:15], v[4:5]
	s_nop 0
	v_pk_mul_f32 v[4:5], v[12:13], v[4:5]
	s_nop 0
	v_cvt_pk_bf16_f32 v11, v4, v5
	global_store_dwordx2 v[8:9], v[10:11], off offset:144
	v_mov_b32_e32 v4, v40
	v_mov_b32_e32 v5, v41
	s_nop 0
	v_mov_b32_e32 v10, v212
	v_mov_b32_e32 v11, v213
	v_mov_b32_e32 v12, v214
	v_mov_b32_e32 v13, v215
	v_lshlrev_b32_e32 v14, 16, v4
	v_and_b32_e32 v15, 0xffff0000, v4
	v_mul_f32_e32 v4, 0xbfb8aa3b, v14
	v_exp_f32_e32 v4, v4
	v_pk_mul_f32 v[10:11], v[18:19], v[10:11]
	v_add_f32_e32 v4, 1.0, v4
	v_rcp_f32_e32 v16, v4
	v_mul_f32_e32 v4, 0xbfb8aa3b, v15
	v_exp_f32_e32 v4, v4
	s_nop 0
	v_add_f32_e32 v4, 1.0, v4
	v_rcp_f32_e32 v17, v4
	v_lshlrev_b32_e32 v4, 16, v5
	v_mul_f32_e32 v7, 0xbfb8aa3b, v4
	v_exp_f32_e32 v7, v7
	v_pk_mul_f32 v[14:15], v[16:17], v[14:15]
	v_and_b32_e32 v5, 0xffff0000, v5
	v_pk_mul_f32 v[10:11], v[10:11], v[14:15]
	v_add_f32_e32 v7, 1.0, v7
	v_rcp_f32_e32 v14, v7
	v_pk_mul_f32 v[16:17], v[92:93], v[6:7] op_sel_hi:[1,0]
	v_mul_f32_e32 v7, 0xbfb8aa3b, v5
	v_exp_f32_e32 v7, v7
	v_pk_mul_f32 v[12:13], v[16:17], v[12:13]
	v_cvt_pk_bf16_f32 v10, v10, v11
	v_add_f32_e32 v7, 1.0, v7
	v_rcp_f32_e32 v15, v7
	v_pk_mul_f32 v[18:19], v[94:95], v[6:7] op_sel_hi:[1,0]
	v_pk_mul_f32 v[4:5], v[14:15], v[4:5]
	s_nop 0
	v_pk_mul_f32 v[4:5], v[12:13], v[4:5]
	s_nop 0
	v_cvt_pk_bf16_f32 v11, v4, v5
	global_store_dwordx2 v[8:9], v[10:11], off offset:160
	v_mov_b32_e32 v4, v42
	v_mov_b32_e32 v5, v43
	s_nop 0
	v_mov_b32_e32 v10, v216
	v_mov_b32_e32 v11, v217
	v_mov_b32_e32 v12, v218
	v_mov_b32_e32 v13, v219
	v_lshlrev_b32_e32 v14, 16, v4
	v_and_b32_e32 v15, 0xffff0000, v4
	v_mul_f32_e32 v4, 0xbfb8aa3b, v14
	v_exp_f32_e32 v4, v4
	v_pk_mul_f32 v[10:11], v[18:19], v[10:11]
	v_add_f32_e32 v4, 1.0, v4
	v_rcp_f32_e32 v16, v4
	v_mul_f32_e32 v4, 0xbfb8aa3b, v15
	v_exp_f32_e32 v4, v4
	s_nop 0
	v_add_f32_e32 v4, 1.0, v4
	v_rcp_f32_e32 v17, v4
	v_lshlrev_b32_e32 v4, 16, v5
	v_mul_f32_e32 v7, 0xbfb8aa3b, v4
	v_exp_f32_e32 v7, v7
	v_pk_mul_f32 v[14:15], v[16:17], v[14:15]
	v_and_b32_e32 v5, 0xffff0000, v5
	v_pk_mul_f32 v[10:11], v[10:11], v[14:15]
	v_add_f32_e32 v7, 1.0, v7
	v_rcp_f32_e32 v14, v7
	v_pk_mul_f32 v[16:17], v[96:97], v[6:7] op_sel_hi:[1,0]
	v_mul_f32_e32 v7, 0xbfb8aa3b, v5
	v_exp_f32_e32 v7, v7
	v_pk_mul_f32 v[12:13], v[16:17], v[12:13]
	v_cvt_pk_bf16_f32 v10, v10, v11
	v_add_f32_e32 v7, 1.0, v7
	v_rcp_f32_e32 v15, v7
	v_pk_mul_f32 v[18:19], v[66:67], v[6:7] op_sel_hi:[1,0]
	v_pk_mul_f32 v[4:5], v[14:15], v[4:5]
	s_nop 0
	v_pk_mul_f32 v[4:5], v[12:13], v[4:5]
	s_nop 0
	v_cvt_pk_bf16_f32 v11, v4, v5
	global_store_dwordx2 v[8:9], v[10:11], off offset:176
	v_mov_b32_e32 v4, v44
	v_mov_b32_e32 v5, v45
	s_nop 0
	v_mov_b32_e32 v10, v220
	v_mov_b32_e32 v11, v221
	v_mov_b32_e32 v12, v222
	v_mov_b32_e32 v13, v223
	v_lshlrev_b32_e32 v14, 16, v4
	v_and_b32_e32 v15, 0xffff0000, v4
	v_mul_f32_e32 v4, 0xbfb8aa3b, v14
	v_exp_f32_e32 v4, v4
	v_pk_mul_f32 v[10:11], v[18:19], v[10:11]
	v_add_f32_e32 v4, 1.0, v4
	v_rcp_f32_e32 v16, v4
	v_mul_f32_e32 v4, 0xbfb8aa3b, v15
	v_exp_f32_e32 v4, v4
	s_nop 0
	v_add_f32_e32 v4, 1.0, v4
	v_rcp_f32_e32 v17, v4
	v_lshlrev_b32_e32 v4, 16, v5
	v_mul_f32_e32 v7, 0xbfb8aa3b, v4
	v_exp_f32_e32 v7, v7
	v_pk_mul_f32 v[14:15], v[16:17], v[14:15]
	v_and_b32_e32 v5, 0xffff0000, v5
	v_pk_mul_f32 v[10:11], v[10:11], v[14:15]
	v_add_f32_e32 v7, 1.0, v7
; __device__ __forceinline__ unsigned cvt_pk_bf16(float lo, float hi) { f32x2_t v = {lo, hi}; bf16x2_t b = __builtin_convertvector(v, bf16x2_t); return __builtin_bit_cast(unsigned, b); }
; __device__ __forceinline__ float bf_lo(unsigned w) { return __uint_as_float(w << 16); }
; __device__ __forceinline__ float bf_hi(unsigned w) { return __uint_as_float(w & 0xffff0000u); }
; __device__ __forceinline__ float silu_f(float z) { return z * __builtin_amdgcn_rcpf(1.0f + fast_exp2(-1.4426950408889634f * z)); }
; __device__ __forceinline__ void diff_unit(LAS unsigned char* lds, const bf16_t* __restrict__ u, bf16_t* __restrict__ yz, float* __restrict__ oscr, const unsigned* __restrict__ kb, int b, int h, int qb, float lam, float slope2, const float* __restrict__ gsub, float out_scale) {
;     ...
; #pragma unroll
;       for (int c = 0; c < 4; ++c)
; #pragma unroll
;         for (int g = 0; g < 4; ++g) { const u32x2 zz = *(const u32x2*)(zp + 32 * c + 8 * g); const f32x4 gg = *(const f32x4*)(gp + 32 * c + 8 * g);
;             const float a0 = o[c][4 * g + 0] * rs * gg[0] * silu_f(bf_lo(zz.x)), a1 = o[c][4 * g + 1] * rs * gg[1] * silu_f(bf_hi(zz.x));
;             const float a2 = o[c][4 * g + 2] * rs * gg[2] * silu_f(bf_lo(zz.y)), a3 = o[c][4 * g + 3] * rs * gg[3] * silu_f(bf_hi(zz.y));
;             u32x2 w; w.x = cvt_pk_bf16(a0, a1); w.y = cvt_pk_bf16(a2, a3); *(u32x2*)(yp + 32 * c + 8 * g) = w; } }
;     asm volatile("s_waitcnt vmcnt(0)" ::: "memory");
	v_rcp_f32_e32 v14, v7
	v_pk_mul_f32 v[16:17], v[68:69], v[6:7] op_sel_hi:[1,0]
	v_mul_f32_e32 v7, 0xbfb8aa3b, v5
	v_exp_f32_e32 v7, v7
	v_pk_mul_f32 v[12:13], v[16:17], v[12:13]
	v_cvt_pk_bf16_f32 v10, v10, v11
	v_add_f32_e32 v7, 1.0, v7
	v_rcp_f32_e32 v15, v7
	v_pk_mul_f32 v[18:19], v[70:71], v[6:7] op_sel_hi:[1,0]
	v_pk_mul_f32 v[4:5], v[14:15], v[4:5]
	s_nop 0
	v_pk_mul_f32 v[4:5], v[12:13], v[4:5]
	s_nop 0
	v_cvt_pk_bf16_f32 v11, v4, v5
	global_store_dwordx2 v[8:9], v[10:11], off offset:192
	v_mov_b32_e32 v4, v46
	v_mov_b32_e32 v5, v47
	s_nop 0
	v_mov_b32_e32 v10, v224
	v_mov_b32_e32 v11, v225
	v_mov_b32_e32 v12, v226
	v_mov_b32_e32 v13, v227
	v_lshlrev_b32_e32 v14, 16, v4
	v_and_b32_e32 v15, 0xffff0000, v4
	v_mul_f32_e32 v4, 0xbfb8aa3b, v14
	v_exp_f32_e32 v4, v4
	v_pk_mul_f32 v[10:11], v[18:19], v[10:11]
	v_add_f32_e32 v4, 1.0, v4
	v_rcp_f32_e32 v16, v4
	v_mul_f32_e32 v4, 0xbfb8aa3b, v15
	v_exp_f32_e32 v4, v4
	s_nop 0
	v_add_f32_e32 v4, 1.0, v4
	v_rcp_f32_e32 v17, v4
	v_lshlrev_b32_e32 v4, 16, v5
	v_mul_f32_e32 v7, 0xbfb8aa3b, v4
	v_exp_f32_e32 v7, v7
	v_pk_mul_f32 v[14:15], v[16:17], v[14:15]
	v_and_b32_e32 v5, 0xffff0000, v5
	v_pk_mul_f32 v[10:11], v[10:11], v[14:15]
	v_add_f32_e32 v7, 1.0, v7
	v_rcp_f32_e32 v14, v7
	v_pk_mul_f32 v[16:17], v[72:73], v[6:7] op_sel_hi:[1,0]
	v_mul_f32_e32 v7, 0xbfb8aa3b, v5
	v_exp_f32_e32 v7, v7
	v_pk_mul_f32 v[12:13], v[16:17], v[12:13]
	v_cvt_pk_bf16_f32 v10, v10, v11
	v_add_f32_e32 v7, 1.0, v7
	v_rcp_f32_e32 v15, v7
	v_pk_mul_f32 v[18:19], v[74:75], v[6:7] op_sel_hi:[1,0]
	v_pk_mul_f32 v[4:5], v[14:15], v[4:5]
	s_nop 0
	v_pk_mul_f32 v[4:5], v[12:13], v[4:5]
	s_nop 0
	v_cvt_pk_bf16_f32 v11, v4, v5
	global_store_dwordx2 v[8:9], v[10:11], off offset:208
	v_mov_b32_e32 v4, v48
	v_mov_b32_e32 v5, v49
	s_nop 0
	v_mov_b32_e32 v10, v52
	v_mov_b32_e32 v11, v53
	v_mov_b32_e32 v12, v54
	v_mov_b32_e32 v13, v55
	v_lshlrev_b32_e32 v14, 16, v4
	v_and_b32_e32 v15, 0xffff0000, v4
	v_mul_f32_e32 v4, 0xbfb8aa3b, v14
	v_exp_f32_e32 v4, v4
	v_pk_mul_f32 v[10:11], v[18:19], v[10:11]
	v_add_f32_e32 v4, 1.0, v4
	v_rcp_f32_e32 v16, v4
	v_mul_f32_e32 v4, 0xbfb8aa3b, v15
	v_exp_f32_e32 v4, v4
	s_nop 0
	v_add_f32_e32 v4, 1.0, v4
	v_rcp_f32_e32 v17, v4
	v_lshlrev_b32_e32 v4, 16, v5
	v_mul_f32_e32 v7, 0xbfb8aa3b, v4
	v_exp_f32_e32 v7, v7
	v_pk_mul_f32 v[14:15], v[16:17], v[14:15]
	v_and_b32_e32 v5, 0xffff0000, v5
	v_pk_mul_f32 v[10:11], v[10:11], v[14:15]
	v_add_f32_e32 v7, 1.0, v7
	v_rcp_f32_e32 v14, v7
	v_pk_mul_f32 v[16:17], v[76:77], v[6:7] op_sel_hi:[1,0]
	v_mul_f32_e32 v7, 0xbfb8aa3b, v5
	v_exp_f32_e32 v7, v7
	v_pk_mul_f32 v[12:13], v[16:17], v[12:13]
	v_cvt_pk_bf16_f32 v10, v10, v11
	v_add_f32_e32 v7, 1.0, v7
	v_rcp_f32_e32 v15, v7
	v_pk_mul_f32 v[16:17], v[78:79], v[6:7] op_sel_hi:[1,0]
	v_pk_mul_f32 v[6:7], v[80:81], v[6:7] op_sel_hi:[1,0]
	v_pk_mul_f32 v[4:5], v[14:15], v[4:5]
	s_nop 0
	v_pk_mul_f32 v[4:5], v[12:13], v[4:5]
	s_nop 0
	v_cvt_pk_bf16_f32 v11, v4, v5
	global_store_dwordx2 v[8:9], v[10:11], off offset:224
	v_mov_b32_e32 v10, v50
	v_mov_b32_e32 v11, v51
	s_nop 0
	v_mov_b32_e32 v2, v56
	v_mov_b32_e32 v3, v57
	v_mov_b32_e32 v4, v58
	v_mov_b32_e32 v5, v59
	v_lshlrev_b32_e32 v12, 16, v10
	v_mul_f32_e32 v0, 0xbfb8aa3b, v12
	v_exp_f32_e32 v0, v0
	v_and_b32_e32 v13, 0xffff0000, v10
	v_lshlrev_b32_e32 v10, 16, v11
	v_pk_mul_f32 v[2:3], v[16:17], v[2:3]
	v_add_f32_e32 v0, 1.0, v0
	v_rcp_f32_e32 v14, v0
	v_mul_f32_e32 v0, 0xbfb8aa3b, v13
	v_exp_f32_e32 v0, v0
	v_and_b32_e32 v11, 0xffff0000, v11
	v_pk_mul_f32 v[4:5], v[6:7], v[4:5]
	v_add_f32_e32 v0, 1.0, v0
	v_rcp_f32_e32 v15, v0
	v_mul_f32_e32 v0, 0xbfb8aa3b, v10
	v_exp_f32_e32 v0, v0
	v_pk_mul_f32 v[12:13], v[14:15], v[12:13]
	s_nop 0
	v_pk_mul_f32 v[2:3], v[2:3], v[12:13]
	v_add_f32_e32 v0, 1.0, v0
	v_rcp_f32_e32 v12, v0
	v_mul_f32_e32 v0, 0xbfb8aa3b, v11
	v_exp_f32_e32 v0, v0
	v_cvt_pk_bf16_f32 v2, v2, v3
	v_add_f32_e32 v0, 1.0, v0
	v_rcp_f32_e32 v13, v0
	s_nop 0
	v_pk_mul_f32 v[6:7], v[12:13], v[10:11]
	s_nop 0
	v_pk_mul_f32 v[4:5], v[4:5], v[6:7]
	s_nop 0
	v_cvt_pk_bf16_f32 v3, v4, v5
	global_store_dwordx2 v[8:9], v[2:3], off offset:240
	s_waitcnt vmcnt(0)

; __device__ __forceinline__ unsigned cvt_pk_bf16(float lo, float hi) { f32x2_t v = {lo, hi}; bf16x2_t b = __builtin_convertvector(v, bf16x2_t); return __builtin_bit_cast(unsigned, b); }
; __device__ __forceinline__ float bf_lo(unsigned w) { return __uint_as_float(w << 16); }
; __device__ __forceinline__ float bf_hi(unsigned w) { return __uint_as_float(w & 0xffff0000u); }
; __device__ __forceinline__ float silu_f(float z) { return z * __builtin_amdgcn_rcpf(1.0f + fast_exp2(-1.4426950408889634f * z)); }
; __device__ __forceinline__ void sb_unit(LAS unsigned char* lds, const bf16_t* __restrict__ u, bf16_t* __restrict__ yz, int b, int h, int qb) {
;     ...
;     { const bf16_t* zp = u + (rowbase + t_row) * NIN + 3 * DM + h * 64 + 4 * hi;
;       bf16_t* yp = yz + (rowbase + t_row) * DM + h * 64 + 4 * hi;
; #pragma unroll
;       for (int c = 0; c < 2; ++c)
; #pragma unroll
;         for (int g = 0; g < 4; ++g) { const u32x2 zz = *(const u32x2*)(zp + 32 * c + 8 * g);
;             const float a0 = (c ? o1 : o0)[4 * g + 0] * silu_f(bf_lo(zz.x)), a1 = (c ? o1 : o0)[4 * g + 1] * silu_f(bf_hi(zz.x));
;             const float a2 = (c ? o1 : o0)[4 * g + 2] * silu_f(bf_lo(zz.y)), a3 = (c ? o1 : o0)[4 * g + 3] * silu_f(bf_hi(zz.y));
;             u32x2 w; w.x = cvt_pk_bf16(a0, a1); w.y = cvt_pk_bf16(a2, a3); *(u32x2*)(yp + 32 * c + 8 * g) = w; } }
.LBB0_297:
	s_lshl_b32 s96, s16, 1
	v_lshl_add_u64 v[34:35], v[84:85], 0, s[96:97]
	v_mov_b32_e32 v87, v1
	v_lshl_add_u64 v[38:39], v[34:35], 0, v[86:87]
	s_mov_b64 s[4:5], 0x1800
	v_lshl_add_u64 v[36:37], v[38:39], 0, s[4:5]
	global_load_dwordx2 v[112:113], v[36:37], off
	global_load_dwordx2 v[114:115], v[36:37], off offset:16
	global_load_dwordx2 v[116:117], v[36:37], off offset:32
	global_load_dwordx2 v[118:119], v[36:37], off offset:48
	global_load_dwordx2 v[120:121], v[36:37], off offset:64
	global_load_dwordx2 v[122:123], v[36:37], off offset:80
	global_load_dwordx2 v[124:125], v[36:37], off offset:96
	global_load_dwordx2 v[126:127], v[36:37], off offset:112
	v_add_co_u32_e32 v38, vcc, 0x1000, v38
	v_readlane_b32 s4, v233, 39
	s_nop 0
	v_addc_co_u32_e32 v39, vcc, 0, v39, vcc
	v_lshlrev_b64 v[34:35], 11, v[82:83]
	v_readlane_b32 s5, v233, 40
	s_add_i32 s14, s14, s38
	s_add_i32 s3, s3, s38
	v_lshl_add_u64 v[34:35], s[4:5], 0, v[34:35]
	v_lshl_add_u64 v[34:35], v[34:35], 0, s[96:97]
	v_lshl_add_u64 v[34:35], v[34:35], 0, v[86:87]
	s_cmpk_gt_i32 s14, 0x7ff
	s_waitcnt vmcnt(0)
	v_mov_b32_e32 v38, v112
	v_mov_b32_e32 v39, v113
	v_lshlrev_b32_e32 v40, 16, v38
	v_mul_f32_e32 v0, 0xbfb8aa3b, v40
	v_exp_f32_e32 v0, v0
	v_and_b32_e32 v41, 0xffff0000, v38
	v_lshlrev_b32_e32 v38, 16, v39
	v_and_b32_e32 v39, 0xffff0000, v39
	v_add_f32_e32 v0, 1.0, v0
	v_rcp_f32_e32 v42, v0
	v_mul_f32_e32 v0, 0xbfb8aa3b, v41
	v_exp_f32_e32 v0, v0
	s_nop 0
	v_add_f32_e32 v0, 1.0, v0
	v_rcp_f32_e32 v43, v0
	v_mul_f32_e32 v0, 0xbfb8aa3b, v38
	v_exp_f32_e32 v0, v0
	v_pk_mul_f32 v[40:41], v[42:43], v[40:41]
	s_nop 0
	v_pk_mul_f32 v[18:19], v[18:19], v[40:41]
	v_add_f32_e32 v0, 1.0, v0
	v_rcp_f32_e32 v40, v0
	v_mul_f32_e32 v0, 0xbfb8aa3b, v39
	v_exp_f32_e32 v0, v0
	v_cvt_pk_bf16_f32 v18, v18, v19
	v_add_f32_e32 v0, 1.0, v0
	v_rcp_f32_e32 v41, v0
	s_nop 0
	v_pk_mul_f32 v[38:39], v[40:41], v[38:39]
	s_nop 0
	v_pk_mul_f32 v[20:21], v[20:21], v[38:39]
	s_nop 0
	v_cvt_pk_bf16_f32 v19, v20, v21
	global_store_dwordx2 v[34:35], v[18:19], off
	v_mov_b32_e32 v18, v114
	v_mov_b32_e32 v19, v115
	v_lshlrev_b32_e32 v20, 16, v18
	v_mul_f32_e32 v0, 0xbfb8aa3b, v20
	v_exp_f32_e32 v0, v0
	v_and_b32_e32 v21, 0xffff0000, v18
	v_lshlrev_b32_e32 v18, 16, v19
	v_and_b32_e32 v19, 0xffff0000, v19
	v_add_f32_e32 v0, 1.0, v0
	v_rcp_f32_e32 v38, v0
	v_mul_f32_e32 v0, 0xbfb8aa3b, v21
	v_exp_f32_e32 v0, v0
	s_nop 0
	v_add_f32_e32 v0, 1.0, v0
	v_rcp_f32_e32 v39, v0
	v_mul_f32_e32 v0, 0xbfb8aa3b, v18
	v_exp_f32_e32 v0, v0
	v_pk_mul_f32 v[20:21], v[38:39], v[20:21]
	s_nop 0
	v_pk_mul_f32 v[20:21], v[22:23], v[20:21]
	v_add_f32_e32 v0, 1.0, v0
	v_rcp_f32_e32 v22, v0
	v_mul_f32_e32 v0, 0xbfb8aa3b, v19
	v_exp_f32_e32 v0, v0
	v_cvt_pk_bf16_f32 v20, v20, v21
	v_add_f32_e32 v0, 1.0, v0
	v_rcp_f32_e32 v23, v0
	s_nop 0
	v_pk_mul_f32 v[18:19], v[22:23], v[18:19]
	s_nop 0
	v_pk_mul_f32 v[18:19], v[24:25], v[18:19]
	s_nop 0
	v_cvt_pk_bf16_f32 v21, v18, v19
	v_mov_b32_e32 v18, v116
	v_mov_b32_e32 v19, v117
	s_nop 0
	global_store_dwordx2 v[34:35], v[20:21], off offset:16
	v_lshlrev_b32_e32 v20, 16, v18
	v_mul_f32_e32 v0, 0xbfb8aa3b, v20
	v_exp_f32_e32 v0, v0
	v_and_b32_e32 v21, 0xffff0000, v18
	v_lshlrev_b32_e32 v18, 16, v19
	v_and_b32_e32 v19, 0xffff0000, v19
	v_add_f32_e32 v0, 1.0, v0
	v_rcp_f32_e32 v22, v0
	v_mul_f32_e32 v0, 0xbfb8aa3b, v21
	v_exp_f32_e32 v0, v0
	s_nop 0
	v_add_f32_e32 v0, 1.0, v0
	v_rcp_f32_e32 v23, v0
	v_mul_f32_e32 v0, 0xbfb8aa3b, v18
	v_exp_f32_e32 v0, v0
	v_pk_mul_f32 v[20:21], v[22:23], v[20:21]
	s_nop 0
	v_pk_mul_f32 v[20:21], v[26:27], v[20:21]
	v_add_f32_e32 v0, 1.0, v0
	v_rcp_f32_e32 v22, v0
	v_mul_f32_e32 v0, 0xbfb8aa3b, v19
	v_exp_f32_e32 v0, v0
	v_cvt_pk_bf16_f32 v20, v20, v21
	v_add_f32_e32 v0, 1.0, v0
	v_rcp_f32_e32 v23, v0
	s_nop 0
	v_pk_mul_f32 v[18:19], v[22:23], v[18:19]
	s_nop 0
	v_pk_mul_f32 v[18:19], v[28:29], v[18:19]
	s_nop 0
	v_cvt_pk_bf16_f32 v21, v18, v19
	v_mov_b32_e32 v18, v118
	v_mov_b32_e32 v19, v119
	s_nop 0
	global_store_dwordx2 v[34:35], v[20:21], off offset:32
	v_lshlrev_b32_e32 v20, 16, v18
	v_mul_f32_e32 v0, 0xbfb8aa3b, v20
	v_exp_f32_e32 v0, v0
	v_and_b32_e32 v21, 0xffff0000, v18
	v_lshlrev_b32_e32 v18, 16, v19
	v_and_b32_e32 v19, 0xffff0000, v19
	v_add_f32_e32 v0, 1.0, v0
	v_rcp_f32_e32 v22, v0
	v_mul_f32_e32 v0, 0xbfb8aa3b, v21
	v_exp_f32_e32 v0, v0
; __device__ __forceinline__ unsigned cvt_pk_bf16(float lo, float hi) { f32x2_t v = {lo, hi}; bf16x2_t b = __builtin_convertvector(v, bf16x2_t); return __builtin_bit_cast(unsigned, b); }
; __device__ __forceinline__ float bf_lo(unsigned w) { return __uint_as_float(w << 16); }
; __device__ __forceinline__ float bf_hi(unsigned w) { return __uint_as_float(w & 0xffff0000u); }
; __device__ __forceinline__ float silu_f(float z) { return z * __builtin_amdgcn_rcpf(1.0f + fast_exp2(-1.4426950408889634f * z)); }
; __device__ __forceinline__ void sb_unit(LAS unsigned char* lds, const bf16_t* __restrict__ u, bf16_t* __restrict__ yz, int b, int h, int qb) {
;     ...
;     { const bf16_t* zp = u + (rowbase + t_row) * NIN + 3 * DM + h * 64 + 4 * hi;
;       bf16_t* yp = yz + (rowbase + t_row) * DM + h * 64 + 4 * hi;
; #pragma unroll
;       for (int c = 0; c < 2; ++c)
; #pragma unroll
;         for (int g = 0; g < 4; ++g) { const u32x2 zz = *(const u32x2*)(zp + 32 * c + 8 * g);
;             const float a0 = (c ? o1 : o0)[4 * g + 0] * silu_f(bf_lo(zz.x)), a1 = (c ? o1 : o0)[4 * g + 1] * silu_f(bf_hi(zz.x));
;             const float a2 = (c ? o1 : o0)[4 * g + 2] * silu_f(bf_lo(zz.y)), a3 = (c ? o1 : o0)[4 * g + 3] * silu_f(bf_hi(zz.y));
;             u32x2 w; w.x = cvt_pk_bf16(a0, a1); w.y = cvt_pk_bf16(a2, a3); *(u32x2*)(yp + 32 * c + 8 * g) = w; } }
	s_nop 0
	v_add_f32_e32 v0, 1.0, v0
	v_rcp_f32_e32 v23, v0
	v_mul_f32_e32 v0, 0xbfb8aa3b, v18
	v_exp_f32_e32 v0, v0
	v_pk_mul_f32 v[20:21], v[22:23], v[20:21]
	s_nop 0
	v_pk_mul_f32 v[20:21], v[30:31], v[20:21]
	v_add_f32_e32 v0, 1.0, v0
	v_rcp_f32_e32 v22, v0
	v_mul_f32_e32 v0, 0xbfb8aa3b, v19
	v_exp_f32_e32 v0, v0
	v_cvt_pk_bf16_f32 v20, v20, v21
	v_add_f32_e32 v0, 1.0, v0
	v_rcp_f32_e32 v23, v0
	s_nop 0
	v_pk_mul_f32 v[18:19], v[22:23], v[18:19]
	s_nop 0
	v_pk_mul_f32 v[18:19], v[32:33], v[18:19]
	s_nop 0
	v_cvt_pk_bf16_f32 v21, v18, v19
	v_mov_b32_e32 v18, v120
	v_mov_b32_e32 v19, v121
	s_nop 0
	global_store_dwordx2 v[34:35], v[20:21], off offset:48
	v_lshlrev_b32_e32 v20, 16, v18
	v_mul_f32_e32 v0, 0xbfb8aa3b, v20
	v_exp_f32_e32 v0, v0
	v_and_b32_e32 v21, 0xffff0000, v18
	v_lshlrev_b32_e32 v18, 16, v19
	v_and_b32_e32 v19, 0xffff0000, v19
	v_add_f32_e32 v0, 1.0, v0
	v_rcp_f32_e32 v22, v0
	v_mul_f32_e32 v0, 0xbfb8aa3b, v21
	v_exp_f32_e32 v0, v0
	s_nop 0
	v_add_f32_e32 v0, 1.0, v0
	v_rcp_f32_e32 v23, v0
	v_mul_f32_e32 v0, 0xbfb8aa3b, v18
	v_exp_f32_e32 v0, v0
	v_pk_mul_f32 v[20:21], v[22:23], v[20:21]
	s_nop 0
	v_pk_mul_f32 v[2:3], v[2:3], v[20:21]
	v_add_f32_e32 v0, 1.0, v0
	v_rcp_f32_e32 v20, v0
	v_mul_f32_e32 v0, 0xbfb8aa3b, v19
	v_exp_f32_e32 v0, v0
	v_cvt_pk_bf16_f32 v2, v2, v3
	v_add_f32_e32 v0, 1.0, v0
	v_rcp_f32_e32 v21, v0
	s_nop 0
	v_pk_mul_f32 v[18:19], v[20:21], v[18:19]
	s_nop 0
	v_pk_mul_f32 v[4:5], v[4:5], v[18:19]
	s_nop 0
	v_cvt_pk_bf16_f32 v3, v4, v5
	global_store_dwordx2 v[34:35], v[2:3], off offset:64
	v_mov_b32_e32 v2, v122
	v_mov_b32_e32 v3, v123
	v_lshlrev_b32_e32 v4, 16, v2
	v_mul_f32_e32 v0, 0xbfb8aa3b, v4
	v_exp_f32_e32 v0, v0
	v_and_b32_e32 v5, 0xffff0000, v2
	v_lshlrev_b32_e32 v2, 16, v3
	v_and_b32_e32 v3, 0xffff0000, v3
	v_add_f32_e32 v0, 1.0, v0
	v_rcp_f32_e32 v18, v0
	v_mul_f32_e32 v0, 0xbfb8aa3b, v5
	v_exp_f32_e32 v0, v0
	s_nop 0
	v_add_f32_e32 v0, 1.0, v0
	v_rcp_f32_e32 v19, v0
	v_mul_f32_e32 v0, 0xbfb8aa3b, v2
	v_exp_f32_e32 v0, v0
	v_pk_mul_f32 v[4:5], v[18:19], v[4:5]
	s_nop 0
	v_pk_mul_f32 v[4:5], v[6:7], v[4:5]
	v_add_f32_e32 v0, 1.0, v0
	v_rcp_f32_e32 v6, v0
	v_mul_f32_e32 v0, 0xbfb8aa3b, v3
	v_exp_f32_e32 v0, v0
	v_cvt_pk_bf16_f32 v4, v4, v5
	v_add_f32_e32 v0, 1.0, v0
	v_rcp_f32_e32 v7, v0
	s_nop 0
	v_pk_mul_f32 v[2:3], v[6:7], v[2:3]
	s_nop 0
	v_pk_mul_f32 v[2:3], v[8:9], v[2:3]
	s_nop 0
	v_cvt_pk_bf16_f32 v5, v2, v3
	v_mov_b32_e32 v2, v124
	v_mov_b32_e32 v3, v125
	s_nop 0
	global_store_dwordx2 v[34:35], v[4:5], off offset:80
	v_lshlrev_b32_e32 v4, 16, v2
	v_mul_f32_e32 v0, 0xbfb8aa3b, v4
	v_exp_f32_e32 v0, v0
	v_and_b32_e32 v5, 0xffff0000, v2
	v_lshlrev_b32_e32 v2, 16, v3
	v_and_b32_e32 v3, 0xffff0000, v3
	v_add_f32_e32 v0, 1.0, v0
	v_rcp_f32_e32 v6, v0
	v_mul_f32_e32 v0, 0xbfb8aa3b, v5
	v_exp_f32_e32 v0, v0
	s_nop 0
	v_add_f32_e32 v0, 1.0, v0
	v_rcp_f32_e32 v7, v0
	v_mul_f32_e32 v0, 0xbfb8aa3b, v2
	v_exp_f32_e32 v0, v0
	v_pk_mul_f32 v[4:5], v[6:7], v[4:5]
	s_nop 0
	v_pk_mul_f32 v[4:5], v[10:11], v[4:5]
	v_add_f32_e32 v0, 1.0, v0
	v_rcp_f32_e32 v6, v0
	v_mul_f32_e32 v0, 0xbfb8aa3b, v3
	v_exp_f32_e32 v0, v0
	v_cvt_pk_bf16_f32 v4, v4, v5
	v_add_f32_e32 v0, 1.0, v0
	v_rcp_f32_e32 v7, v0
	s_nop 0
	v_pk_mul_f32 v[2:3], v[6:7], v[2:3]
	s_nop 0
	v_pk_mul_f32 v[2:3], v[12:13], v[2:3]
	s_nop 0
	v_cvt_pk_bf16_f32 v5, v2, v3
	v_mov_b32_e32 v2, v126
	v_mov_b32_e32 v3, v127
	s_nop 0
	global_store_dwordx2 v[34:35], v[4:5], off offset:96
	v_lshlrev_b32_e32 v4, 16, v2
	v_mul_f32_e32 v0, 0xbfb8aa3b, v4
	v_exp_f32_e32 v0, v0
	v_and_b32_e32 v5, 0xffff0000, v2
	v_lshlrev_b32_e32 v2, 16, v3
	v_and_b32_e32 v3, 0xffff0000, v3
	v_add_f32_e32 v0, 1.0, v0
	v_rcp_f32_e32 v6, v0
	v_mul_f32_e32 v0, 0xbfb8aa3b, v5
	v_exp_f32_e32 v0, v0
	s_nop 0
	v_add_f32_e32 v0, 1.0, v0
	v_rcp_f32_e32 v7, v0
	v_mul_f32_e32 v0, 0xbfb8aa3b, v2
	v_exp_f32_e32 v0, v0
	v_pk_mul_f32 v[4:5], v[6:7], v[4:5]
	s_nop 0
	v_pk_mul_f32 v[4:5], v[14:15], v[4:5]
	v_add_f32_e32 v0, 1.0, v0
	v_rcp_f32_e32 v6, v0
	v_mul_f32_e32 v0, 0xbfb8aa3b, v3
	v_exp_f32_e32 v0, v0
	v_cvt_pk_bf16_f32 v4, v4, v5
	v_add_f32_e32 v0, 1.0, v0
	v_rcp_f32_e32 v7, v0
	s_nop 0
	v_pk_mul_f32 v[2:3], v[6:7], v[2:3]
	s_nop 0
	v_pk_mul_f32 v[2:3], v[16:17], v[2:3]
	s_nop 0
	v_cvt_pk_bf16_f32 v5, v2, v3
	global_store_dwordx2 v[34:35], v[4:5], off offset:112
	s_cbranch_scc1 .LBB0_293
